# adaLN modulation: silu(c) loop as 18 loads in flight under one wait (was 18 serial rounds)
# baseline (speedup 1.0000x reference)
.LBB0_5:
	s_or_b64 exec, exec, s[6:7]
	s_cmpk_gt_i32 s82, 0xbf
	s_cbranch_scc1 .LBB0_18
	s_load_dwordx2 s[16:17], s[84:85], 0x8
	s_load_dwordx2 s[18:19], s[84:85], 0x18
	v_lshlrev_b32_e32 v2, 2, v246
	s_waitcnt lgkmcnt(0)
	global_load_dword v20, v2, s[16:17]
	v_add_u32_e32 v3, 0x800, v2
	global_load_dword v21, v3, s[16:17]
	v_add_u32_e32 v3, 0x1000, v2
	global_load_dword v22, v3, s[16:17]
	v_add_u32_e32 v3, 0x1800, v2
	global_load_dword v23, v3, s[16:17]
	v_add_u32_e32 v3, 0x2000, v2
	global_load_dword v24, v3, s[16:17]
	v_add_u32_e32 v3, 0x2800, v2
	global_load_dword v25, v3, s[16:17]
	v_add_u32_e32 v3, 0x3000, v2
	global_load_dword v26, v3, s[16:17]
	v_add_u32_e32 v3, 0x3800, v2
	global_load_dword v27, v3, s[16:17]
	v_add_u32_e32 v3, 0x4000, v2
	global_load_dword v28, v3, s[16:17]
	v_add_u32_e32 v3, 0x4800, v2
	global_load_dword v29, v3, s[16:17]
	v_add_u32_e32 v3, 0x5000, v2
	global_load_dword v30, v3, s[16:17]
	v_add_u32_e32 v3, 0x5800, v2
	global_load_dword v31, v3, s[16:17]
	v_add_u32_e32 v3, 0x6000, v2
	global_load_dword v32, v3, s[16:17]
	v_add_u32_e32 v3, 0x6800, v2
	global_load_dword v33, v3, s[16:17]
	v_add_u32_e32 v3, 0x7000, v2
	global_load_dword v34, v3, s[16:17]
	v_add_u32_e32 v3, 0x7800, v2
	global_load_dword v35, v3, s[16:17]
	global_load_dword v36, v2, s[18:19]
	global_load_dword v37, v2, s[18:19] offset:2048
	v_add_u32_e32 v1, 0, v2
	s_waitcnt vmcnt(0)
	v_mul_f32_e32 v7, 0xbfb8aa3b, v20
	v_exp_f32_e32 v7, v7
	s_nop 0
	v_add_f32_e32 v4, 1.0, v7
	v_div_scale_f32 v7, s[12:13], v4, v4, v20
	v_rcp_f32_e32 v9, v7
	v_div_scale_f32 v10, vcc, v20, v4, v20
	v_fma_f32 v11, -v7, v9, 1.0
	v_fmac_f32_e32 v9, v11, v9
	v_mul_f32_e32 v11, v10, v9
	v_fma_f32 v12, -v7, v11, v10
	v_fmac_f32_e32 v11, v12, v9
	v_fma_f32 v7, -v7, v11, v10
	v_div_fmas_f32 v7, v7, v9, v11
	v_div_fixup_f32 v4, v7, v4, v20
	ds_write_b32 v1, v4
	v_mul_f32_e32 v7, 0xbfb8aa3b, v21
	v_exp_f32_e32 v7, v7
	s_nop 0
	v_add_f32_e32 v4, 1.0, v7
	v_div_scale_f32 v7, s[12:13], v4, v4, v21
	v_rcp_f32_e32 v9, v7
	v_div_scale_f32 v10, vcc, v21, v4, v21
	v_fma_f32 v11, -v7, v9, 1.0
	v_fmac_f32_e32 v9, v11, v9
	v_mul_f32_e32 v11, v10, v9
	v_fma_f32 v12, -v7, v11, v10
	v_fmac_f32_e32 v11, v12, v9
	v_fma_f32 v7, -v7, v11, v10
	v_div_fmas_f32 v7, v7, v9, v11
	v_div_fixup_f32 v4, v7, v4, v21
	ds_write_b32 v1, v4 offset:2048
	v_mul_f32_e32 v7, 0xbfb8aa3b, v22
	v_exp_f32_e32 v7, v7
	s_nop 0
	v_add_f32_e32 v4, 1.0, v7
	v_div_scale_f32 v7, s[12:13], v4, v4, v22
	v_rcp_f32_e32 v9, v7
	v_div_scale_f32 v10, vcc, v22, v4, v22
	v_fma_f32 v11, -v7, v9, 1.0
	v_fmac_f32_e32 v9, v11, v9
	v_mul_f32_e32 v11, v10, v9
	v_fma_f32 v12, -v7, v11, v10
	v_fmac_f32_e32 v11, v12, v9
	v_fma_f32 v7, -v7, v11, v10
	v_div_fmas_f32 v7, v7, v9, v11
	v_div_fixup_f32 v4, v7, v4, v22
	ds_write_b32 v1, v4 offset:4096
	v_mul_f32_e32 v7, 0xbfb8aa3b, v23
	v_exp_f32_e32 v7, v7
	s_nop 0
	v_add_f32_e32 v4, 1.0, v7
	v_div_scale_f32 v7, s[12:13], v4, v4, v23
	v_rcp_f32_e32 v9, v7
	v_div_scale_f32 v10, vcc, v23, v4, v23
	v_fma_f32 v11, -v7, v9, 1.0
	v_fmac_f32_e32 v9, v11, v9
	v_mul_f32_e32 v11, v10, v9
	v_fma_f32 v12, -v7, v11, v10
	v_fmac_f32_e32 v11, v12, v9
	v_fma_f32 v7, -v7, v11, v10
	v_div_fmas_f32 v7, v7, v9, v11
	v_div_fixup_f32 v4, v7, v4, v23
	ds_write_b32 v1, v4 offset:6144
	v_mul_f32_e32 v7, 0xbfb8aa3b, v24
	v_exp_f32_e32 v7, v7
	s_nop 0
	v_add_f32_e32 v4, 1.0, v7
	v_div_scale_f32 v7, s[12:13], v4, v4, v24
	v_rcp_f32_e32 v9, v7
	v_div_scale_f32 v10, vcc, v24, v4, v24
	v_fma_f32 v11, -v7, v9, 1.0
	v_fmac_f32_e32 v9, v11, v9
	v_mul_f32_e32 v11, v10, v9
	v_fma_f32 v12, -v7, v11, v10
	v_fmac_f32_e32 v11, v12, v9
	v_fma_f32 v7, -v7, v11, v10
	v_div_fmas_f32 v7, v7, v9, v11
	v_div_fixup_f32 v4, v7, v4, v24
	ds_write_b32 v1, v4 offset:8192
	v_mul_f32_e32 v7, 0xbfb8aa3b, v25
	v_exp_f32_e32 v7, v7
	s_nop 0
	v_add_f32_e32 v4, 1.0, v7
	v_div_scale_f32 v7, s[12:13], v4, v4, v25
	v_rcp_f32_e32 v9, v7
	v_div_scale_f32 v10, vcc, v25, v4, v25
	v_fma_f32 v11, -v7, v9, 1.0
	v_fmac_f32_e32 v9, v11, v9
	v_mul_f32_e32 v11, v10, v9
	v_fma_f32 v12, -v7, v11, v10
	v_fmac_f32_e32 v11, v12, v9
	v_fma_f32 v7, -v7, v11, v10
	v_div_fmas_f32 v7, v7, v9, v11
	v_div_fixup_f32 v4, v7, v4, v25
	ds_write_b32 v1, v4 offset:10240
	v_mul_f32_e32 v7, 0xbfb8aa3b, v26
	v_exp_f32_e32 v7, v7
	s_nop 0
	v_add_f32_e32 v4, 1.0, v7
	v_div_scale_f32 v7, s[12:13], v4, v4, v26
	v_rcp_f32_e32 v9, v7
	v_div_scale_f32 v10, vcc, v26, v4, v26
	v_fma_f32 v11, -v7, v9, 1.0
	v_fmac_f32_e32 v9, v11, v9
	v_mul_f32_e32 v11, v10, v9
	v_fma_f32 v12, -v7, v11, v10
	v_fmac_f32_e32 v11, v12, v9
	v_fma_f32 v7, -v7, v11, v10
	v_div_fmas_f32 v7, v7, v9, v11
	v_div_fixup_f32 v4, v7, v4, v26
	ds_write_b32 v1, v4 offset:12288
	v_mul_f32_e32 v7, 0xbfb8aa3b, v27
	v_exp_f32_e32 v7, v7
	s_nop 0
	v_add_f32_e32 v4, 1.0, v7
	v_div_scale_f32 v7, s[12:13], v4, v4, v27
	v_rcp_f32_e32 v9, v7
	v_div_scale_f32 v10, vcc, v27, v4, v27
	v_fma_f32 v11, -v7, v9, 1.0
	v_fmac_f32_e32 v9, v11, v9
	v_mul_f32_e32 v11, v10, v9
	v_fma_f32 v12, -v7, v11, v10
	v_fmac_f32_e32 v11, v12, v9
	v_fma_f32 v7, -v7, v11, v10
	v_div_fmas_f32 v7, v7, v9, v11
	v_div_fixup_f32 v4, v7, v4, v27
	ds_write_b32 v1, v4 offset:14336
	v_mul_f32_e32 v7, 0xbfb8aa3b, v28
	v_exp_f32_e32 v7, v7
	s_nop 0
	v_add_f32_e32 v4, 1.0, v7
	v_div_scale_f32 v7, s[12:13], v4, v4, v28
	v_rcp_f32_e32 v9, v7
	v_div_scale_f32 v10, vcc, v28, v4, v28
	v_fma_f32 v11, -v7, v9, 1.0
	v_fmac_f32_e32 v9, v11, v9
	v_mul_f32_e32 v11, v10, v9
	v_fma_f32 v12, -v7, v11, v10
	v_fmac_f32_e32 v11, v12, v9
	v_fma_f32 v7, -v7, v11, v10
	v_div_fmas_f32 v7, v7, v9, v11
	v_div_fixup_f32 v4, v7, v4, v28
	ds_write_b32 v1, v4 offset:16384
	v_mul_f32_e32 v7, 0xbfb8aa3b, v29
	v_exp_f32_e32 v7, v7
	s_nop 0
	v_add_f32_e32 v4, 1.0, v7
	v_div_scale_f32 v7, s[12:13], v4, v4, v29
	v_rcp_f32_e32 v9, v7
	v_div_scale_f32 v10, vcc, v29, v4, v29
	v_fma_f32 v11, -v7, v9, 1.0
	v_fmac_f32_e32 v9, v11, v9
	v_mul_f32_e32 v11, v10, v9
	v_fma_f32 v12, -v7, v11, v10
	v_fmac_f32_e32 v11, v12, v9
	v_fma_f32 v7, -v7, v11, v10
	v_div_fmas_f32 v7, v7, v9, v11
	v_div_fixup_f32 v4, v7, v4, v29
	ds_write_b32 v1, v4 offset:18432
	v_mul_f32_e32 v7, 0xbfb8aa3b, v30
	v_exp_f32_e32 v7, v7
	s_nop 0
	v_add_f32_e32 v4, 1.0, v7
	v_div_scale_f32 v7, s[12:13], v4, v4, v30
	v_rcp_f32_e32 v9, v7
	v_div_scale_f32 v10, vcc, v30, v4, v30
	v_fma_f32 v11, -v7, v9, 1.0
	v_fmac_f32_e32 v9, v11, v9
	v_mul_f32_e32 v11, v10, v9
	v_fma_f32 v12, -v7, v11, v10
	v_fmac_f32_e32 v11, v12, v9
	v_fma_f32 v7, -v7, v11, v10
	v_div_fmas_f32 v7, v7, v9, v11
	v_div_fixup_f32 v4, v7, v4, v30
	ds_write_b32 v1, v4 offset:20480
	v_mul_f32_e32 v7, 0xbfb8aa3b, v31
	v_exp_f32_e32 v7, v7
	s_nop 0
	v_add_f32_e32 v4, 1.0, v7
	v_div_scale_f32 v7, s[12:13], v4, v4, v31
	v_rcp_f32_e32 v9, v7
	v_div_scale_f32 v10, vcc, v31, v4, v31
	v_fma_f32 v11, -v7, v9, 1.0
	v_fmac_f32_e32 v9, v11, v9
	v_mul_f32_e32 v11, v10, v9
	v_fma_f32 v12, -v7, v11, v10
	v_fmac_f32_e32 v11, v12, v9
	v_fma_f32 v7, -v7, v11, v10
	v_div_fmas_f32 v7, v7, v9, v11
	v_div_fixup_f32 v4, v7, v4, v31
	ds_write_b32 v1, v4 offset:22528
	v_mul_f32_e32 v7, 0xbfb8aa3b, v32
	v_exp_f32_e32 v7, v7
	s_nop 0
	v_add_f32_e32 v4, 1.0, v7
	v_div_scale_f32 v7, s[12:13], v4, v4, v32
	v_rcp_f32_e32 v9, v7
	v_div_scale_f32 v10, vcc, v32, v4, v32
	v_fma_f32 v11, -v7, v9, 1.0
	v_fmac_f32_e32 v9, v11, v9
	v_mul_f32_e32 v11, v10, v9
	v_fma_f32 v12, -v7, v11, v10
	v_fmac_f32_e32 v11, v12, v9
	v_fma_f32 v7, -v7, v11, v10
	v_div_fmas_f32 v7, v7, v9, v11
	v_div_fixup_f32 v4, v7, v4, v32
	ds_write_b32 v1, v4 offset:24576
	v_mul_f32_e32 v7, 0xbfb8aa3b, v33
	v_exp_f32_e32 v7, v7
	s_nop 0
	v_add_f32_e32 v4, 1.0, v7
	v_div_scale_f32 v7, s[12:13], v4, v4, v33
	v_rcp_f32_e32 v9, v7
	v_div_scale_f32 v10, vcc, v33, v4, v33
	v_fma_f32 v11, -v7, v9, 1.0
	v_fmac_f32_e32 v9, v11, v9
	v_mul_f32_e32 v11, v10, v9
	v_fma_f32 v12, -v7, v11, v10
	v_fmac_f32_e32 v11, v12, v9
	v_fma_f32 v7, -v7, v11, v10
	v_div_fmas_f32 v7, v7, v9, v11
	v_div_fixup_f32 v4, v7, v4, v33
	ds_write_b32 v1, v4 offset:26624
	v_mul_f32_e32 v7, 0xbfb8aa3b, v34
	v_exp_f32_e32 v7, v7
	s_nop 0
	v_add_f32_e32 v4, 1.0, v7
	v_div_scale_f32 v7, s[12:13], v4, v4, v34
	v_rcp_f32_e32 v9, v7
	v_div_scale_f32 v10, vcc, v34, v4, v34
	v_fma_f32 v11, -v7, v9, 1.0
	v_fmac_f32_e32 v9, v11, v9
	v_mul_f32_e32 v11, v10, v9
	v_fma_f32 v12, -v7, v11, v10
	v_fmac_f32_e32 v11, v12, v9
	v_fma_f32 v7, -v7, v11, v10
	v_div_fmas_f32 v7, v7, v9, v11
	v_div_fixup_f32 v4, v7, v4, v34
	ds_write_b32 v1, v4 offset:28672
	v_mul_f32_e32 v7, 0xbfb8aa3b, v35
	v_exp_f32_e32 v7, v7
	s_nop 0
	v_add_f32_e32 v4, 1.0, v7
	v_div_scale_f32 v7, s[12:13], v4, v4, v35
	v_rcp_f32_e32 v9, v7
	v_div_scale_f32 v10, vcc, v35, v4, v35
	v_fma_f32 v11, -v7, v9, 1.0
	v_fmac_f32_e32 v9, v11, v9
	v_mul_f32_e32 v11, v10, v9
	v_fma_f32 v12, -v7, v11, v10
	v_fmac_f32_e32 v11, v12, v9
	v_fma_f32 v7, -v7, v11, v10
	v_div_fmas_f32 v7, v7, v9, v11
	v_div_fixup_f32 v4, v7, v4, v35
	ds_write_b32 v1, v4 offset:30720
	v_mul_f32_e32 v7, 0xbfb8aa3b, v36
	v_exp_f32_e32 v7, v7
	s_nop 0
	v_add_f32_e32 v4, 1.0, v7
	v_div_scale_f32 v7, s[12:13], v4, v4, v36
	v_rcp_f32_e32 v9, v7
	v_div_scale_f32 v10, vcc, v36, v4, v36
	v_fma_f32 v11, -v7, v9, 1.0
	v_fmac_f32_e32 v9, v11, v9
	v_mul_f32_e32 v11, v10, v9
	v_fma_f32 v12, -v7, v11, v10
	v_fmac_f32_e32 v11, v12, v9
	v_fma_f32 v7, -v7, v11, v10
	v_div_fmas_f32 v7, v7, v9, v11
	v_div_fixup_f32 v4, v7, v4, v36
	ds_write_b32 v1, v4 offset:32768
	v_mul_f32_e32 v7, 0xbfb8aa3b, v37
	v_exp_f32_e32 v7, v7
	s_nop 0
	v_add_f32_e32 v4, 1.0, v7
	v_div_scale_f32 v7, s[12:13], v4, v4, v37
	v_rcp_f32_e32 v9, v7
	v_div_scale_f32 v10, vcc, v37, v4, v37
	v_fma_f32 v11, -v7, v9, 1.0
	v_fmac_f32_e32 v9, v11, v9
	v_mul_f32_e32 v11, v10, v9
	v_fma_f32 v12, -v7, v11, v10
	v_fmac_f32_e32 v11, v12, v9
	v_fma_f32 v7, -v7, v11, v10
	v_div_fmas_f32 v7, v7, v9, v11
	v_div_fixup_f32 v4, v7, v4, v37
	ds_write_b32 v1, v4 offset:34816
.LBB0_12:
	s_mul_hi_i32 s6, s82, 0x2aaaaaab
	s_lshr_b32 s7, s6, 31
	s_ashr_i32 s6, s6, 4
	s_add_i32 s14, s6, s7
	s_mul_i32 s6, s14, 0x60
	s_sub_i32 s6, s82, s6
	s_lshl_b32 s6, s6, 6
	s_ashr_i32 s7, s6, 31
	s_mul_i32 s13, s14, 0x1800000
	s_lshl_b64 s[8:9], s[6:7], 2
	s_waitcnt lgkmcnt(0)
	s_barrier
	s_load_dwordx2 s[10:11], s[84:85], 0x20
	s_mul_hi_i32 s12, s14, 0x1800000
	s_add_u32 s6, s8, s13
	s_addc_u32 s7, s9, s12
	v_and_b32_e32 v6, 63, v246
	v_lshrrev_b32_e32 v2, 6, v246
	s_movk_i32 s15, 0x6000
	v_mov_b64_e32 v[8:9], s[6:7]
	v_mul_hi_u32_u24_e32 v5, 0x6000, v2
	v_mul_u32_u24_e32 v4, 0x6000, v2
	v_mad_u64_u32 v[8:9], s[6:7], v2, s15, v[8:9]
	v_lshlrev_b32_e32 v2, 2, v6
	v_or_b32_e32 v8, v8, v2
	v_mov_b32_e32 v3, 0
	v_lshrrev_b32_e32 v1, 6, v246
	s_waitcnt lgkmcnt(0)
	v_lshl_add_u64 v[8:9], s[10:11], 0, v[8:9]
	s_mov_b64 s[6:7], 0x150000
	v_or_b32_e32 v7, 0xffffffc0, v1
	v_lshl_add_u32 v28, v1, 2, 0
	v_lshl_add_u64 v[8:9], v[8:9], 0, s[6:7]
	s_mov_b64 s[10:11], 0
	s_mov_b64 s[12:13], 0x180000
	s_movk_i32 s15, 0x3bf
	v_mov_b32_e32 v10, v3
	v_mov_b32_e32 v11, v3
	v_mov_b32_e32 v12, v3
	v_mov_b32_e32 v13, v3
	v_mov_b32_e32 v14, v3
	v_mov_b32_e32 v15, v3
	v_mov_b32_e32 v16, v3
	v_mov_b32_e32 v17, v3
	v_mov_b32_e32 v29, v3
